# grid barrier: the cache invalidate is issued at every second barrier only (any stale copy dates from at least two phases back, so one of two consecutive barriers suffices); the other barriers only war
# speedup vs baseline: 1.0098x; 1.0098x over previous
; __device__ __forceinline__ unsigned xb_ld(unsigned* p)              { return __hip_atomic_load(p, __ATOMIC_RELAXED, __HIP_MEMORY_SCOPE_AGENT); }
; __device__ __forceinline__ unsigned xb_add(unsigned* p, unsigned v) { return __hip_atomic_fetch_add(p, v, __ATOMIC_RELAXED, __HIP_MEMORY_SCOPE_AGENT); }
; #define XB_SPIN(cond, bar) do { unsigned _sp = 0; while (cond) { __builtin_amdgcn_s_sleep(1); \
;     if ((++_sp & 255u) == 0u) { if (xb_ld(&(bar)[XB_TMO])) break; if (_sp > XB_SPIN_CAP) { atomicAdd(&(bar)[XB_TMO], 1u); break; } } } } while (0)
; __device__ __forceinline__ void xcd_barrier(const XcdBarrier& b) {
;     ...
;             __builtin_amdgcn_fence(__ATOMIC_ACQUIRE, "agent");
;             xb_add(&bar[XB_XGEN(b.x)], 1u);
;             asm volatile("s_waitcnt vmcnt(0)" ::: "memory");
;         } else {
;             XB_SPIN(xb_ld(&bar[XB_XGEN(b.x)]) == gen, bar);
;             __builtin_amdgcn_fence(__ATOMIC_ACQUIRE, "agent");
;             asm volatile("s_waitcnt vmcnt(0)" ::: "memory");
;         }
;     }
;     __syncthreads();
.Linit_done:
	s_or_b64 exec, exec, s[4:5]
	s_waitcnt vmcnt(0)
	s_waitcnt lgkmcnt(0)
	s_barrier
	v_readfirstlane_b32 s2, v152
	s_cmp_lg_u32 s2, 64
	s_cbranch_scc1 .Leinv_skip_0
	s_getpc_b64 s[2:3]

; __device__ __forceinline__ unsigned xb_ld(unsigned* p)              { return __hip_atomic_load(p, __ATOMIC_RELAXED, __HIP_MEMORY_SCOPE_AGENT); }
; __device__ __forceinline__ unsigned xb_add(unsigned* p, unsigned v) { return __hip_atomic_fetch_add(p, v, __ATOMIC_RELAXED, __HIP_MEMORY_SCOPE_AGENT); }
; #define XB_SPIN(cond, bar) do { unsigned _sp = 0; while (cond) { __builtin_amdgcn_s_sleep(1); \
;     if ((++_sp & 255u) == 0u) { if (xb_ld(&(bar)[XB_TMO])) break; if (_sp > XB_SPIN_CAP) { atomicAdd(&(bar)[XB_TMO], 1u); break; } } } } while (0)
; __device__ __forceinline__ void xcd_barrier(const XcdBarrier& b) {
;     ...
;             __builtin_amdgcn_fence(__ATOMIC_ACQUIRE, "agent");
;             xb_add(&bar[XB_XGEN(b.x)], 1u);
;             asm volatile("s_waitcnt vmcnt(0)" ::: "memory");
;         } else {
;             XB_SPIN(xb_ld(&bar[XB_XGEN(b.x)]) == gen, bar);
;             __builtin_amdgcn_fence(__ATOMIC_ACQUIRE, "agent");
;             asm volatile("s_waitcnt vmcnt(0)" ::: "memory");
;         }
;     }
;     __syncthreads();
.LBB0_395:
	s_waitcnt vmcnt(0)
	s_waitcnt lgkmcnt(0)
	s_barrier
	v_readfirstlane_b32 s2, v152
	s_cmp_lg_u32 s2, 64
	s_cbranch_scc1 .Leinv_skip_2
	s_getpc_b64 s[2:3]

; __device__ __forceinline__ unsigned xb_ld(unsigned* p)              { return __hip_atomic_load(p, __ATOMIC_RELAXED, __HIP_MEMORY_SCOPE_AGENT); }
; __device__ __forceinline__ unsigned xb_add(unsigned* p, unsigned v) { return __hip_atomic_fetch_add(p, v, __ATOMIC_RELAXED, __HIP_MEMORY_SCOPE_AGENT); }
; #define XB_SPIN(cond, bar) do { unsigned _sp = 0; while (cond) { __builtin_amdgcn_s_sleep(1); \
;     if ((++_sp & 255u) == 0u) { if (xb_ld(&(bar)[XB_TMO])) break; if (_sp > XB_SPIN_CAP) { atomicAdd(&(bar)[XB_TMO], 1u); break; } } } } while (0)
; __device__ __forceinline__ void xcd_barrier(const XcdBarrier& b) {
;     ...
;             __builtin_amdgcn_fence(__ATOMIC_ACQUIRE, "agent");
;             xb_add(&bar[XB_XGEN(b.x)], 1u);
;             asm volatile("s_waitcnt vmcnt(0)" ::: "memory");
;         } else {
;             XB_SPIN(xb_ld(&bar[XB_XGEN(b.x)]) == gen, bar);
;             __builtin_amdgcn_fence(__ATOMIC_ACQUIRE, "agent");
;             asm volatile("s_waitcnt vmcnt(0)" ::: "memory");
;         }
;     }
;     __syncthreads();
.LBB0_977:
	s_waitcnt vmcnt(0)
	s_barrier
	v_readfirstlane_b32 s2, v152
	s_cmp_lg_u32 s2, 64
	s_cbranch_scc1 .Leinv_skip_4
	s_getpc_b64 s[2:3]

; __device__ __forceinline__ unsigned xb_ld(unsigned* p)              { return __hip_atomic_load(p, __ATOMIC_RELAXED, __HIP_MEMORY_SCOPE_AGENT); }
; __device__ __forceinline__ unsigned xb_add(unsigned* p, unsigned v) { return __hip_atomic_fetch_add(p, v, __ATOMIC_RELAXED, __HIP_MEMORY_SCOPE_AGENT); }
; #define XB_SPIN(cond, bar) do { unsigned _sp = 0; while (cond) { __builtin_amdgcn_s_sleep(1); \
;     if ((++_sp & 255u) == 0u) { if (xb_ld(&(bar)[XB_TMO])) break; if (_sp > XB_SPIN_CAP) { atomicAdd(&(bar)[XB_TMO], 1u); break; } } } } while (0)
; __device__ __forceinline__ void xcd_barrier(const XcdBarrier& b) {
;     ...
;             __builtin_amdgcn_fence(__ATOMIC_ACQUIRE, "agent");
;             xb_add(&bar[XB_XGEN(b.x)], 1u);
;             asm volatile("s_waitcnt vmcnt(0)" ::: "memory");
;         } else {
;             XB_SPIN(xb_ld(&bar[XB_XGEN(b.x)]) == gen, bar);
;             __builtin_amdgcn_fence(__ATOMIC_ACQUIRE, "agent");
;             asm volatile("s_waitcnt vmcnt(0)" ::: "memory");
;         }
;     }
;     __syncthreads();
.LBB0_1367:
	s_waitcnt vmcnt(0)
	s_waitcnt vmcnt(0)
	s_barrier
	v_readfirstlane_b32 s2, v152
	s_cmp_lg_u32 s2, 64
	s_cbranch_scc1 .Leinv_skip_8
	s_getpc_b64 s[2:3]
